# gate/up GEMM main loop: LDS-DMA addresses in scalar-base form (SALU adds) instead of sixteen 64-bit VALU adds per iteration
# speedup vs baseline: 1.0115x; 1.0025x over previous
; #define PG8_STAGE(bufoff, gbase, voff) do { _Pragma("unroll") for (int _i = 0; _i < 2; ++_i) \
;         __builtin_amdgcn_global_load_lds((const unsigned*)((const char*)(gbase) + (voff)[_i]), (LAS unsigned*)(lds + (bufoff) + ldsw + _i * 8192), 16, 0, 0); } while (0)
; #define PG8_LDA(dst, b, h) do { _Pragma("unroll") for (int m = 0; m < 4; ++m) _Pragma("unroll") for (int k = 0; k < 2; ++k) dst[m][k] = *(const LAS bf16x8*)(lds + PG8_SA(b, h) + aoff + m * 2048 + k * 1024); } while (0)
; #define PG8_LDB(dst, b, h) do { _Pragma("unroll") for (int n = 0; n < 2; ++n) _Pragma("unroll") for (int k = 0; k < 2; ++k) dst[n][k] = *(const LAS bf16x8*)(lds + PG8_SB(b, h) + boff + n * 2048 + k * 1024); } while (0)
; #define PG8_MMA(ai, bj, At, Bt) do { __builtin_amdgcn_s_setprio(1); _Pragma("unroll") for (int m = 0; m < 4; ++m) _Pragma("unroll") for (int n = 0; n < 2; ++n) _Pragma("unroll") for (int k = 0; k < 2; ++k) \
;         acc[ai][bj][m][n] = __builtin_amdgcn_mfma_f32_16x16x32_bf16(Bt[n][k], At[m][k], acc[ai][bj][m][n], 0, 0, 0); __builtin_amdgcn_s_setprio(0); } while (0)
; #define PG8_WAIT_V(n) asm volatile("s_waitcnt vmcnt(" #n ")" ::: "memory")
; #define PG8_WAIT_L(n) asm volatile("s_waitcnt lgkmcnt(" #n ")" ::: "memory")
; #define PG8_BAR __builtin_amdgcn_s_barrier()
; #define PG8_SCHED __builtin_amdgcn_sched_barrier(0)
; template <class Epi, class Sched, bool ALIGN_EPI>
; DI void gemm_phase(LAS unsigned char* lds, const Gemm g, const Sched& S, const Epi& E) {
;     ...
;         for (int t = 0; t < nt; t += 2) {
;             const bool last = (t == nt - 2);
;             const char* a1 = cA + (size_t)(t + 1) * kstep;
;             const char* a2 = last ? nA : cA + (size_t)(t + 2) * kstep; const char* b2 = last ? nB : cB + (size_t)(t + 2) * kstep;
;             const char* a3 = a2 + kstep; const char* b3 = b2 + kstep;
;             PG8_LDB(B0, 0, 0); PG8_LDB(B1, 0, 1); PG8_SCHED; PG8_LDA(At, 0, 0); PG8_STAGE(PG8_SA(1, 1), a1 + hstep, voffA);
;             PG8_WAIT_V(8); PG8_WAIT_L(0); PG8_BAR; PG8_MMA(0, 0, At, B0); PG8_MMA(0, 1, At, B1); PG8_BAR; PG8_SCHED;
;             PG8_LDA(At, 0, 1); PG8_STAGE(PG8_SB(0, 0), b2, voffA); PG8_STAGE(PG8_SB(0, 1), b2 + hstep, voffA); PG8_STAGE(PG8_SA(0, 0), a2, voffA);
;             PG8_WAIT_V(8); PG8_WAIT_L(0); PG8_BAR; PG8_MMA(1, 0, At, B0); PG8_MMA(1, 1, At, B1); PG8_BAR; PG8_SCHED;
.LBB0_826:
	s_add_u32 s30, s0, 0xfffc0080
	s_addc_u32 s31, s1, -1
	s_add_i32 s46, 0, 0x10000
	s_cmp_eq_u32 s45, 12
	s_cselect_b32 s35, s25, s31
	s_cselect_b32 s34, s24, s30
	s_cselect_b32 s31, s23, s44
	s_cselect_b32 s30, s29, s43
	s_add_i32 s52, 0, 0x14000
	v_add_u32_e32 v56, s46, v241
	v_add_u32_e32 v136, s52, v241
	ds_read_b128 v[44:47], v56
	ds_read_b128 v[48:51], v56 offset:1024
	ds_read_b128 v[52:55], v56 offset:2048
	ds_read_b128 v[56:59], v56 offset:3072
	ds_read_b128 v[124:127], v136
	ds_read_b128 v[128:131], v136 offset:1024
	ds_read_b128 v[132:135], v136 offset:2048
	ds_read_b128 v[136:139], v136 offset:3072
	s_add_i32 m0, s93, 0xc000
	ds_read_b128 v[160:163], v245
	ds_read_b128 v[164:167], v245 offset:1024
	ds_read_b128 v[182:185], v245 offset:2048
	ds_read_b128 v[186:189], v245 offset:3072
	ds_read_b128 v[190:193], v245 offset:4096
	ds_read_b128 v[194:197], v245 offset:5120
	ds_read_b128 v[198:201], v245 offset:6144
	ds_read_b128 v[202:205], v245 offset:7168
	global_load_lds_dwordx4 v178, s[0:1]
	s_add_i32 m0, s93, 0xe000
	s_nop 0
	global_load_lds_dwordx4 v180, s[0:1]
	s_waitcnt vmcnt(8)
	s_waitcnt lgkmcnt(0)
	s_barrier
	s_setprio 1
	s_waitcnt lgkmcnt(0)
	v_mfma_f32_16x16x32_bf16 v[156:159], v[44:47], v[160:163], v[156:159]
	v_mfma_f32_16x16x32_bf16 v[76:79], v[52:55], v[160:163], v[76:79]
	v_mfma_f32_16x16x32_bf16 v[148:151], v[44:47], v[182:185], v[148:151]
	v_mfma_f32_16x16x32_bf16 v[68:71], v[52:55], v[182:185], v[68:71]
	v_mfma_f32_16x16x32_bf16 v[140:143], v[44:47], v[190:193], v[140:143]
	v_mfma_f32_16x16x32_bf16 v[60:63], v[52:55], v[190:193], v[60:63]
	v_mfma_f32_16x16x32_bf16 v[116:119], v[44:47], v[198:201], v[116:119]
	v_mfma_f32_16x16x32_bf16 v[36:39], v[52:55], v[198:201], v[36:39]
	v_mfma_f32_16x16x32_bf16 v[156:159], v[48:51], v[164:167], v[156:159]
	v_mfma_f32_16x16x32_bf16 v[76:79], v[56:59], v[164:167], v[76:79]
	v_mfma_f32_16x16x32_bf16 v[148:151], v[48:51], v[186:189], v[148:151]
	v_mfma_f32_16x16x32_bf16 v[68:71], v[56:59], v[186:189], v[68:71]
	v_mfma_f32_16x16x32_bf16 v[140:143], v[48:51], v[194:197], v[140:143]
	v_mfma_f32_16x16x32_bf16 v[60:63], v[56:59], v[194:197], v[60:63]
	v_mfma_f32_16x16x32_bf16 v[116:119], v[48:51], v[202:205], v[116:119]
	v_mfma_f32_16x16x32_bf16 v[36:39], v[56:59], v[202:205], v[36:39]
	s_setprio 0
	s_setprio 1
	v_mfma_f32_16x16x32_bf16 v[152:155], v[124:127], v[160:163], v[152:155]
	v_mfma_f32_16x16x32_bf16 v[72:75], v[132:135], v[160:163], v[72:75]
	v_mfma_f32_16x16x32_bf16 v[144:147], v[124:127], v[182:185], v[144:147]
	v_mfma_f32_16x16x32_bf16 v[64:67], v[132:135], v[182:185], v[64:67]
	v_mfma_f32_16x16x32_bf16 v[120:123], v[124:127], v[190:193], v[120:123]
	v_mfma_f32_16x16x32_bf16 v[40:43], v[132:135], v[190:193], v[40:43]
	v_mfma_f32_16x16x32_bf16 v[112:115], v[124:127], v[198:201], v[112:115]
	v_mfma_f32_16x16x32_bf16 v[32:35], v[132:135], v[198:201], v[32:35]
	v_mfma_f32_16x16x32_bf16 v[152:155], v[128:131], v[164:167], v[152:155]
	v_mfma_f32_16x16x32_bf16 v[72:75], v[136:139], v[164:167], v[72:75]
	v_mfma_f32_16x16x32_bf16 v[144:147], v[128:131], v[186:189], v[144:147]
	v_mfma_f32_16x16x32_bf16 v[64:67], v[136:139], v[186:189], v[64:67]
	v_mfma_f32_16x16x32_bf16 v[120:123], v[128:131], v[194:197], v[120:123]
	v_mfma_f32_16x16x32_bf16 v[40:43], v[136:139], v[194:197], v[40:43]
	v_mfma_f32_16x16x32_bf16 v[112:115], v[128:131], v[202:205], v[112:115]
	v_mfma_f32_16x16x32_bf16 v[32:35], v[136:139], v[202:205], v[32:35]
	s_setprio 0
	s_barrier
	s_add_i32 s46, s46, s92
	s_add_u32 s94, s30, s2
	s_addc_u32 s95, s31, s3
	s_add_u32 s96, s34, s2
	s_addc_u32 s97, s35, s3
	s_mov_b32 m0, s46
	ds_read_b128 v[160:163], v245 offset:16384
	ds_read_b128 v[164:167], v245 offset:17408
	ds_read_b128 v[182:185], v245 offset:18432
	ds_read_b128 v[186:189], v245 offset:19456
	ds_read_b128 v[190:193], v245 offset:20480
	ds_read_b128 v[194:197], v245 offset:21504
	ds_read_b128 v[198:201], v245 offset:22528
	ds_read_b128 v[202:205], v245 offset:23552
	global_load_lds_dwordx4 v174, s[30:31]
	s_add_i32 m0, s46, 0x2000
	s_add_u32 s46, s30, 0x40000
	s_addc_u32 s47, s31, 0
	s_add_i32 s52, s52, s92
	global_load_lds_dwordx4 v176, s[30:31]
	s_mov_b32 m0, s52
	s_nop 0
	global_load_lds_dwordx4 v174, s[46:47]
	s_add_i32 m0, s52, 0x2000
	s_nop 0
	global_load_lds_dwordx4 v176, s[46:47]
	s_mov_b32 m0, s93
	s_nop 0
	global_load_lds_dwordx4 v174, s[34:35]
	s_mov_b32 m0, s86
	s_nop 0
	global_load_lds_dwordx4 v176, s[34:35]
	s_waitcnt vmcnt(8)
	s_waitcnt lgkmcnt(0)
	s_barrier
	s_setprio 1
	s_waitcnt lgkmcnt(0)
	v_mfma_f32_16x16x32_bf16 v[108:111], v[44:47], v[160:163], v[108:111]
	v_mfma_f32_16x16x32_bf16 v[28:31], v[52:55], v[160:163], v[28:31]
	v_mfma_f32_16x16x32_bf16 v[100:103], v[44:47], v[182:185], v[100:103]
	v_mfma_f32_16x16x32_bf16 v[20:23], v[52:55], v[182:185], v[20:23]
	v_mfma_f32_16x16x32_bf16 v[92:95], v[44:47], v[190:193], v[92:95]
	v_mfma_f32_16x16x32_bf16 v[12:15], v[52:55], v[190:193], v[12:15]
	v_mfma_f32_16x16x32_bf16 v[4:7], v[52:55], v[198:201], v[4:7]
	v_mfma_f32_16x16x32_bf16 v[108:111], v[48:51], v[164:167], v[108:111]
	v_mfma_f32_16x16x32_bf16 v[28:31], v[56:59], v[164:167], v[28:31]
	v_mfma_f32_16x16x32_bf16 v[100:103], v[48:51], v[186:189], v[100:103]
	v_mfma_f32_16x16x32_bf16 v[20:23], v[56:59], v[186:189], v[20:23]
	v_mfma_f32_16x16x32_bf16 v[92:95], v[48:51], v[194:197], v[92:95]
	v_mfma_f32_16x16x32_bf16 v[12:15], v[56:59], v[194:197], v[12:15]
	v_mfma_f32_16x16x32_bf16 v[44:47], v[44:47], v[198:201], v[84:87]
	v_mfma_f32_16x16x32_bf16 v[4:7], v[56:59], v[202:205], v[4:7]
	v_mfma_f32_16x16x32_bf16 v[44:47], v[48:51], v[202:205], v[44:47]
	s_setprio 0
	s_setprio 1
	v_mfma_f32_16x16x32_bf16 v[24:27], v[132:135], v[160:163], v[24:27]
	v_mfma_f32_16x16x32_bf16 v[16:19], v[132:135], v[182:185], v[16:19]
	v_mfma_f32_16x16x32_bf16 v[8:11], v[132:135], v[190:193], v[8:11]
	v_mfma_f32_16x16x32_bf16 v[80:83], v[124:127], v[198:201], v[80:83]
	v_mfma_f32_16x16x32_bf16 v[0:3], v[132:135], v[198:201], v[0:3]
	v_mfma_f32_16x16x32_bf16 v[48:51], v[124:127], v[160:163], v[104:107]
	v_mfma_f32_16x16x32_bf16 v[24:27], v[136:139], v[164:167], v[24:27]
	v_mfma_f32_16x16x32_bf16 v[52:55], v[124:127], v[182:185], v[96:99]
	v_mfma_f32_16x16x32_bf16 v[16:19], v[136:139], v[186:189], v[16:19]
	v_mfma_f32_16x16x32_bf16 v[56:59], v[124:127], v[190:193], v[88:91]
	v_mfma_f32_16x16x32_bf16 v[8:11], v[136:139], v[194:197], v[8:11]
	v_mfma_f32_16x16x32_bf16 v[80:83], v[128:131], v[202:205], v[80:83]
	v_mfma_f32_16x16x32_bf16 v[0:3], v[136:139], v[202:205], v[0:3]
	v_mfma_f32_16x16x32_bf16 v[48:51], v[128:131], v[164:167], v[48:51]
	v_mfma_f32_16x16x32_bf16 v[52:55], v[128:131], v[186:189], v[52:55]
	v_mfma_f32_16x16x32_bf16 v[56:59], v[128:131], v[194:197], v[56:59]
	s_setprio 0
	s_barrier
; #define PG8_STAGE(bufoff, gbase, voff) do { _Pragma("unroll") for (int _i = 0; _i < 2; ++_i) \
;         __builtin_amdgcn_global_load_lds((const unsigned*)((const char*)(gbase) + (voff)[_i]), (LAS unsigned*)(lds + (bufoff) + ldsw + _i * 8192), 16, 0, 0); } while (0)
; #define PG8_LDA(dst, b, h) do { _Pragma("unroll") for (int m = 0; m < 4; ++m) _Pragma("unroll") for (int k = 0; k < 2; ++k) dst[m][k] = *(const LAS bf16x8*)(lds + PG8_SA(b, h) + aoff + m * 2048 + k * 1024); } while (0)
; #define PG8_LDB(dst, b, h) do { _Pragma("unroll") for (int n = 0; n < 2; ++n) _Pragma("unroll") for (int k = 0; k < 2; ++k) dst[n][k] = *(const LAS bf16x8*)(lds + PG8_SB(b, h) + boff + n * 2048 + k * 1024); } while (0)
; #define PG8_MMA(ai, bj, At, Bt) do { __builtin_amdgcn_s_setprio(1); _Pragma("unroll") for (int m = 0; m < 4; ++m) _Pragma("unroll") for (int n = 0; n < 2; ++n) _Pragma("unroll") for (int k = 0; k < 2; ++k) \
;         acc[ai][bj][m][n] = __builtin_amdgcn_mfma_f32_16x16x32_bf16(Bt[n][k], At[m][k], acc[ai][bj][m][n], 0, 0, 0); __builtin_amdgcn_s_setprio(0); } while (0)
; #define PG8_WAIT_V(n) asm volatile("s_waitcnt vmcnt(" #n ")" ::: "memory")
; #define PG8_WAIT_L(n) asm volatile("s_waitcnt lgkmcnt(" #n ")" ::: "memory")
; #define PG8_BAR __builtin_amdgcn_s_barrier()
; #define PG8_SCHED __builtin_amdgcn_sched_barrier(0)
; template <class Epi, class Sched, bool ALIGN_EPI>
; DI void gemm_phase(LAS unsigned char* lds, const Gemm g, const Sched& S, const Epi& E) {
;     ...
;             PG8_LDB(B0, 1, 0); PG8_LDB(B1, 1, 1); PG8_SCHED; PG8_LDA(At, 1, 0); PG8_STAGE(PG8_SA(0, 1), a2 + hstep, voffA);
;             PG8_WAIT_V(8); PG8_WAIT_L(0); PG8_BAR; PG8_MMA(0, 0, At, B0); PG8_MMA(0, 1, At, B1); PG8_BAR; PG8_SCHED;
;             PG8_LDA(At, 1, 1); PG8_STAGE(PG8_SB(1, 0), b3, voffA); PG8_STAGE(PG8_SB(1, 1), b3 + hstep, voffA); PG8_STAGE(PG8_SA(1, 0), a3, voffA);
;             PG8_WAIT_V(8); PG8_WAIT_L(0); PG8_BAR; PG8_MMA(1, 0, At, B0); PG8_MMA(1, 1, At, B1); PG8_BAR; PG8_SCHED;
;         }
	s_add_i32 s46, 0, 0x18000
	s_add_i32 s47, 0, 0x1c000
	v_add_u32_e32 v104, s46, v241
	v_add_u32_e32 v136, s47, v241
	ds_read_b128 v[84:87], v104
	ds_read_b128 v[88:91], v104 offset:1024
	ds_read_b128 v[96:99], v104 offset:2048
	ds_read_b128 v[104:107], v104 offset:3072
	ds_read_b128 v[124:127], v136
	ds_read_b128 v[128:131], v136 offset:1024
	ds_read_b128 v[132:135], v136 offset:2048
	ds_read_b128 v[136:139], v136 offset:3072
	s_add_u32 s34, s34, 0x40000
	s_addc_u32 s35, s35, 0
	s_mov_b32 m0, s33
	ds_read_b128 v[160:163], v245 offset:32768
	ds_read_b128 v[164:167], v245 offset:33792
	ds_read_b128 v[182:185], v245 offset:34816
	ds_read_b128 v[186:189], v245 offset:35840
	ds_read_b128 v[190:193], v245 offset:36864
	ds_read_b128 v[194:197], v245 offset:37888
	ds_read_b128 v[198:201], v245 offset:38912
	ds_read_b128 v[202:205], v245 offset:39936
	global_load_lds_dwordx4 v174, s[34:35]
	s_mov_b32 m0, s78
	s_nop 0
	global_load_lds_dwordx4 v176, s[34:35]
	s_waitcnt vmcnt(8)
	s_waitcnt lgkmcnt(0)
	s_barrier
	s_setprio 1
	s_waitcnt lgkmcnt(0)
	v_mfma_f32_16x16x32_bf16 v[156:159], v[84:87], v[160:163], v[156:159]
	v_mfma_f32_16x16x32_bf16 v[76:79], v[96:99], v[160:163], v[76:79]
	v_mfma_f32_16x16x32_bf16 v[148:151], v[84:87], v[182:185], v[148:151]
	v_mfma_f32_16x16x32_bf16 v[68:71], v[96:99], v[182:185], v[68:71]
	v_mfma_f32_16x16x32_bf16 v[140:143], v[84:87], v[190:193], v[140:143]
	v_mfma_f32_16x16x32_bf16 v[60:63], v[96:99], v[190:193], v[60:63]
	v_mfma_f32_16x16x32_bf16 v[116:119], v[84:87], v[198:201], v[116:119]
	v_mfma_f32_16x16x32_bf16 v[36:39], v[96:99], v[198:201], v[36:39]
	v_mfma_f32_16x16x32_bf16 v[156:159], v[88:91], v[164:167], v[156:159]
	v_mfma_f32_16x16x32_bf16 v[76:79], v[104:107], v[164:167], v[76:79]
	v_mfma_f32_16x16x32_bf16 v[148:151], v[88:91], v[186:189], v[148:151]
	v_mfma_f32_16x16x32_bf16 v[68:71], v[104:107], v[186:189], v[68:71]
	v_mfma_f32_16x16x32_bf16 v[140:143], v[88:91], v[194:197], v[140:143]
	v_mfma_f32_16x16x32_bf16 v[60:63], v[104:107], v[194:197], v[60:63]
	v_mfma_f32_16x16x32_bf16 v[116:119], v[88:91], v[202:205], v[116:119]
	v_mfma_f32_16x16x32_bf16 v[36:39], v[104:107], v[202:205], v[36:39]
	s_setprio 0
	s_setprio 1
	v_mfma_f32_16x16x32_bf16 v[152:155], v[124:127], v[160:163], v[152:155]
	v_mfma_f32_16x16x32_bf16 v[72:75], v[132:135], v[160:163], v[72:75]
	v_mfma_f32_16x16x32_bf16 v[144:147], v[124:127], v[182:185], v[144:147]
	v_mfma_f32_16x16x32_bf16 v[64:67], v[132:135], v[182:185], v[64:67]
	v_mfma_f32_16x16x32_bf16 v[120:123], v[124:127], v[190:193], v[120:123]
	v_mfma_f32_16x16x32_bf16 v[40:43], v[132:135], v[190:193], v[40:43]
	v_mfma_f32_16x16x32_bf16 v[112:115], v[124:127], v[198:201], v[112:115]
	v_mfma_f32_16x16x32_bf16 v[32:35], v[132:135], v[198:201], v[32:35]
	v_mfma_f32_16x16x32_bf16 v[152:155], v[128:131], v[164:167], v[152:155]
	v_mfma_f32_16x16x32_bf16 v[72:75], v[136:139], v[164:167], v[72:75]
	v_mfma_f32_16x16x32_bf16 v[144:147], v[128:131], v[186:189], v[144:147]
	v_mfma_f32_16x16x32_bf16 v[64:67], v[136:139], v[186:189], v[64:67]
	v_mfma_f32_16x16x32_bf16 v[120:123], v[128:131], v[194:197], v[120:123]
	v_mfma_f32_16x16x32_bf16 v[40:43], v[136:139], v[194:197], v[40:43]
	v_mfma_f32_16x16x32_bf16 v[112:115], v[128:131], v[202:205], v[112:115]
	v_mfma_f32_16x16x32_bf16 v[32:35], v[136:139], v[202:205], v[32:35]
	s_setprio 0
	s_barrier
	s_add_i32 s34, s46, s92
	s_mov_b32 m0, s34
	ds_read_b128 v[160:163], v245 offset:49152
	ds_read_b128 v[164:167], v245 offset:50176
	ds_read_b128 v[182:185], v245 offset:51200
	ds_read_b128 v[186:189], v245 offset:52224
	ds_read_b128 v[190:193], v245 offset:53248
	ds_read_b128 v[194:197], v245 offset:54272
	ds_read_b128 v[198:201], v245 offset:55296
	ds_read_b128 v[202:205], v245 offset:56320
	global_load_lds_dwordx4 v174, s[94:95]
	s_add_i32 m0, s34, 0x2000
	s_add_u32 s30, s30, 0x40080
	s_addc_u32 s31, s31, 0
	s_add_i32 s34, s47, s92
	global_load_lds_dwordx4 v176, s[94:95]
	s_mov_b32 m0, s34
	s_nop 0
	global_load_lds_dwordx4 v174, s[30:31]
	s_add_i32 m0, s34, 0x2000
	s_nop 0
	global_load_lds_dwordx4 v176, s[30:31]
	s_mov_b32 m0, s8
	s_nop 0
	global_load_lds_dwordx4 v174, s[96:97]
	s_mov_b32 m0, s9
	s_nop 0
	global_load_lds_dwordx4 v176, s[96:97]
	s_waitcnt vmcnt(8)
	s_waitcnt lgkmcnt(0)
	s_barrier
	s_setprio 1
	s_waitcnt lgkmcnt(0)
	v_mfma_f32_16x16x32_bf16 v[108:111], v[84:87], v[160:163], v[108:111]
	v_mfma_f32_16x16x32_bf16 v[28:31], v[96:99], v[160:163], v[28:31]
	v_mfma_f32_16x16x32_bf16 v[100:103], v[84:87], v[182:185], v[100:103]
	v_mfma_f32_16x16x32_bf16 v[20:23], v[96:99], v[182:185], v[20:23]
	v_mfma_f32_16x16x32_bf16 v[92:95], v[84:87], v[190:193], v[92:95]
	v_mfma_f32_16x16x32_bf16 v[12:15], v[96:99], v[190:193], v[12:15]
	v_mfma_f32_16x16x32_bf16 v[44:47], v[84:87], v[198:201], v[44:47]
	v_mfma_f32_16x16x32_bf16 v[4:7], v[96:99], v[198:201], v[4:7]
	v_mfma_f32_16x16x32_bf16 v[108:111], v[88:91], v[164:167], v[108:111]
	v_mfma_f32_16x16x32_bf16 v[28:31], v[104:107], v[164:167], v[28:31]
	v_mfma_f32_16x16x32_bf16 v[100:103], v[88:91], v[186:189], v[100:103]
	v_mfma_f32_16x16x32_bf16 v[20:23], v[104:107], v[186:189], v[20:23]
	v_mfma_f32_16x16x32_bf16 v[92:95], v[88:91], v[194:197], v[92:95]
	v_mfma_f32_16x16x32_bf16 v[12:15], v[104:107], v[194:197], v[12:15]
	v_mfma_f32_16x16x32_bf16 v[84:87], v[88:91], v[202:205], v[44:47]
	v_mfma_f32_16x16x32_bf16 v[4:7], v[104:107], v[202:205], v[4:7]
	s_setprio 0
	s_setprio 1
	v_mfma_f32_16x16x32_bf16 v[44:47], v[124:127], v[160:163], v[48:51]
	v_mfma_f32_16x16x32_bf16 v[104:107], v[128:131], v[164:167], v[44:47]
	v_mfma_f32_16x16x32_bf16 v[44:47], v[124:127], v[182:185], v[52:55]
	v_mfma_f32_16x16x32_bf16 v[96:99], v[128:131], v[186:189], v[44:47]
	v_mfma_f32_16x16x32_bf16 v[44:47], v[124:127], v[190:193], v[56:59]
	v_mfma_f32_16x16x32_bf16 v[24:27], v[132:135], v[160:163], v[24:27]
	v_mfma_f32_16x16x32_bf16 v[16:19], v[132:135], v[182:185], v[16:19]
	v_mfma_f32_16x16x32_bf16 v[88:91], v[128:131], v[194:197], v[44:47]
	v_mfma_f32_16x16x32_bf16 v[8:11], v[132:135], v[190:193], v[8:11]
	v_mfma_f32_16x16x32_bf16 v[44:47], v[124:127], v[198:201], v[80:83]
	v_mfma_f32_16x16x32_bf16 v[0:3], v[132:135], v[198:201], v[0:3]
	v_mfma_f32_16x16x32_bf16 v[24:27], v[136:139], v[164:167], v[24:27]
	v_mfma_f32_16x16x32_bf16 v[16:19], v[136:139], v[186:189], v[16:19]
	v_mfma_f32_16x16x32_bf16 v[8:11], v[136:139], v[194:197], v[8:11]
	v_mfma_f32_16x16x32_bf16 v[80:83], v[128:131], v[202:205], v[44:47]
	v_mfma_f32_16x16x32_bf16 v[0:3], v[136:139], v[202:205], v[0:3]
	s_setprio 0
	s_barrier
	s_add_i32 s45, s45, 2
	s_add_u32 s0, s0, 0x100
	s_addc_u32 s1, s1, 0
	s_add_u32 s43, s43, 0x100
	s_addc_u32 s44, s44, 0
	s_cmp_gt_u32 s45, 13
	s_cbranch_scc0 .LBB0_826
	s_and_b64 vcc, exec, s[18:19]
	s_cbranch_vccz .LBB0_829
	s_barrier
